# LRU tile loop: the store-drain wait in front of the scan barrier only on the single tile where the other direction's rows were stored in the same iteration (tile 8 / prompt tile 2)
# baseline (speedup 1.0000x reference)
.LBB0_270:
	s_waitcnt lgkmcnt(0)
	s_barrier
	ds_read_b128 v[40:43], v117
	ds_read_b128 v[36:39], v117 offset:64
	ds_read_b128 v[44:47], v118 offset:9216
	ds_read_b128 v[48:51], v118 offset:18432
	ds_read_b128 v[52:55], v118 offset:9280
	s_waitcnt lgkmcnt(2)
	v_mfma_f32_16x16x32_bf16 v[44:47], v[40:43], v[44:47], 0
	ds_read_u16 v3, v119
	s_waitcnt lgkmcnt(0)
	v_lshlrev_b32_e32 v3, 16, v3
	v_mfma_f32_16x16x32_bf16 v[44:47], v[36:39], v[52:55], v[44:47]
	ds_read_b128 v[52:55], v118 offset:18496
	v_mfma_f32_16x16x32_bf16 v[48:51], v[40:43], v[48:51], 0
	s_waitcnt lgkmcnt(0)
	v_mfma_f32_16x16x32_bf16 v[48:51], v[36:39], v[52:55], v[48:51]
	s_nop 3
	v_add_f32_e32 v1, v97, v44
	v_mul_f32_e32 v1, 0xbfb8aa3b, v1
	v_exp_f32_e32 v1, v1
	s_nop 0
	v_add_f32_e32 v1, 1.0, v1
	v_rcp_f32_e32 v1, v1
	v_add_f32_e32 v2, v98, v48
	v_mul_f32_e32 v2, 0xbfb8aa3b, v2
	v_exp_f32_e32 v2, v2
	v_mul_f32_e32 v1, v105, v1
	v_mul_f32_e32 v1, 0x3fb8aa3b, v1
	v_exp_f32_e32 v1, v1
	v_add_f32_e32 v2, 1.0, v2
	v_rcp_f32_e32 v2, v2
	v_fma_f32 v44, -v1, v1, 1.0
	v_max_f32_e32 v44, 0, v44
	v_sqrt_f32_e32 v44, v44
	v_mul_f32_e32 v2, v2, v3
	v_mul_f32_e32 v2, v2, v44
	ds_write_b32 v109, v1 offset:27648
	ds_write_b32 v109, v2 offset:44288
	v_add_f32_e32 v1, v97, v45
	v_mul_f32_e32 v1, 0xbfb8aa3b, v1
	v_exp_f32_e32 v1, v1
	v_add_f32_e32 v2, v98, v49
	v_mul_f32_e32 v2, 0xbfb8aa3b, v2
	v_exp_f32_e32 v2, v2
	v_add_f32_e32 v1, 1.0, v1
	v_rcp_f32_e32 v1, v1
	ds_read_u16 v3, v120
	v_add_f32_e32 v2, 1.0, v2
	v_rcp_f32_e32 v2, v2
	v_mul_f32_e32 v1, v105, v1
	v_mul_f32_e32 v1, 0x3fb8aa3b, v1
	v_exp_f32_e32 v1, v1
	s_waitcnt lgkmcnt(0)
	v_lshlrev_b32_e32 v3, 16, v3
	v_mul_f32_e32 v2, v2, v3
	ds_read_u16 v3, v121
	v_fma_f32 v44, -v1, v1, 1.0
	v_max_f32_e32 v44, 0, v44
	v_sqrt_f32_e32 v44, v44
	s_waitcnt lgkmcnt(0)
	v_lshlrev_b32_e32 v3, 16, v3
	v_mul_f32_e32 v2, v2, v44
	ds_write2st64_b32 v110, v1, v2 offset0:108 offset1:173
	v_add_f32_e32 v1, v97, v46
	v_mul_f32_e32 v1, 0xbfb8aa3b, v1
	v_exp_f32_e32 v1, v1
	v_add_f32_e32 v2, v98, v50
	v_mul_f32_e32 v2, 0xbfb8aa3b, v2
	v_exp_f32_e32 v2, v2
	v_add_f32_e32 v1, 1.0, v1
	v_rcp_f32_e32 v1, v1
	v_add_f32_e32 v2, 1.0, v2
	v_rcp_f32_e32 v2, v2
	v_mul_f32_e32 v1, v105, v1
	v_mul_f32_e32 v1, 0x3fb8aa3b, v1
	v_exp_f32_e32 v1, v1
	v_mul_f32_e32 v2, v2, v3
	v_fma_f32 v44, -v1, v1, 1.0
	v_max_f32_e32 v44, 0, v44
	v_sqrt_f32_e32 v44, v44
	s_nop 0
	v_mul_f32_e32 v2, v2, v44
	ds_write_b32 v111, v1 offset:27648
	ds_write_b32 v111, v2 offset:44288
	v_add_f32_e32 v1, v97, v47
	v_mul_f32_e32 v1, 0xbfb8aa3b, v1
	v_exp_f32_e32 v1, v1
	v_add_f32_e32 v2, v98, v51
	v_mul_f32_e32 v2, 0xbfb8aa3b, v2
	v_exp_f32_e32 v2, v2
	v_add_f32_e32 v1, 1.0, v1
	v_rcp_f32_e32 v1, v1
	ds_read_u16 v3, v122
	v_add_f32_e32 v2, 1.0, v2
	v_rcp_f32_e32 v2, v2
	v_mul_f32_e32 v1, v105, v1
	v_mul_f32_e32 v1, 0x3fb8aa3b, v1
	v_exp_f32_e32 v1, v1
	s_waitcnt lgkmcnt(0)
	v_lshlrev_b32_e32 v3, 16, v3
	v_mul_f32_e32 v2, v2, v3
	ds_read_u16 v3, v124
	v_fma_f32 v44, -v1, v1, 1.0
	v_max_f32_e32 v44, 0, v44
	v_sqrt_f32_e32 v44, v44
	s_waitcnt lgkmcnt(0)
	v_lshlrev_b32_e32 v3, 16, v3
	v_mul_f32_e32 v2, v44, v2
	ds_write2st64_b32 v112, v1, v2 offset0:108 offset1:173
	ds_read_b128 v[48:51], v123 offset:18432
	ds_read_b128 v[44:47], v123 offset:9216
	s_waitcnt lgkmcnt(1)
	v_mfma_f32_16x16x32_bf16 v[52:55], v[40:43], v[48:51], 0
	ds_read_b128 v[48:51], v123 offset:9280
	s_waitcnt lgkmcnt(1)
	v_mfma_f32_16x16x32_bf16 v[44:47], v[40:43], v[44:47], 0
	s_waitcnt lgkmcnt(0)
	v_mfma_f32_16x16x32_bf16 v[48:51], v[36:39], v[48:51], v[44:47]
	s_nop 5
	ds_read_b128 v[44:47], v123 offset:18496
	s_nop 0
	v_add_f32_e32 v1, v99, v48
	v_mul_f32_e32 v1, 0xbfb8aa3b, v1
	v_exp_f32_e32 v1, v1
	s_waitcnt lgkmcnt(0)
	v_mfma_f32_16x16x32_bf16 v[44:47], v[36:39], v[44:47], v[52:55]
	v_add_f32_e32 v1, 1.0, v1
	v_rcp_f32_e32 v1, v1
	s_nop 0
	v_mul_f32_e32 v1, v106, v1
	s_nop 3
	v_add_f32_e32 v2, v100, v44
	v_mul_f32_e32 v2, 0xbfb8aa3b, v2
	v_mul_f32_e32 v1, 0x3fb8aa3b, v1
	v_exp_f32_e32 v2, v2
	v_exp_f32_e32 v1, v1
	v_add_f32_e32 v2, 1.0, v2
	v_fma_f32 v44, -v1, v1, 1.0
	v_rcp_f32_e32 v2, v2
	v_max_f32_e32 v44, 0, v44
	v_sqrt_f32_e32 v44, v44
	v_mul_f32_e32 v2, v2, v3
	v_mul_f32_e32 v2, v2, v44
	ds_write_b32 v109, v1 offset:27712
	ds_write_b32 v109, v2 offset:44352
	v_add_f32_e32 v1, v99, v49
	v_mul_f32_e32 v1, 0xbfb8aa3b, v1
	v_exp_f32_e32 v1, v1
	v_add_f32_e32 v2, v100, v45
	v_mul_f32_e32 v2, 0xbfb8aa3b, v2
	v_exp_f32_e32 v2, v2
	v_add_f32_e32 v1, 1.0, v1
	v_rcp_f32_e32 v1, v1
	ds_read_u16 v3, v125
	v_add_f32_e32 v2, 1.0, v2
	v_rcp_f32_e32 v2, v2
	v_mul_f32_e32 v1, v106, v1
	v_mul_f32_e32 v1, 0x3fb8aa3b, v1
	v_exp_f32_e32 v1, v1
	s_waitcnt lgkmcnt(0)
	v_lshlrev_b32_e32 v3, 16, v3
	v_mul_f32_e32 v2, v2, v3
	v_fma_f32 v44, -v1, v1, 1.0
	v_max_f32_e32 v44, 0, v44
	v_sqrt_f32_e32 v44, v44
	s_nop 0
	v_mul_f32_e32 v2, v2, v44
	ds_write_b32 v113, v1 offset:27712
	ds_write_b32 v113, v2 offset:44352
	v_add_f32_e32 v1, v99, v50
	v_mul_f32_e32 v1, 0xbfb8aa3b, v1
	v_exp_f32_e32 v1, v1
	v_add_f32_e32 v2, v100, v46
	v_mul_f32_e32 v2, 0xbfb8aa3b, v2
	v_exp_f32_e32 v2, v2
	v_add_f32_e32 v1, 1.0, v1
	v_rcp_f32_e32 v1, v1
	ds_read_u16 v3, v126
	v_add_f32_e32 v2, 1.0, v2
	v_rcp_f32_e32 v2, v2
	v_mul_f32_e32 v1, v106, v1
	v_mul_f32_e32 v1, 0x3fb8aa3b, v1
	v_exp_f32_e32 v1, v1
	s_waitcnt lgkmcnt(0)
	v_lshlrev_b32_e32 v3, 16, v3
	v_mul_f32_e32 v2, v2, v3
	v_fma_f32 v44, -v1, v1, 1.0
	v_max_f32_e32 v44, 0, v44
	v_sqrt_f32_e32 v44, v44
	s_nop 0
	v_mul_f32_e32 v2, v2, v44
	ds_write_b32 v111, v1 offset:27712
	ds_write_b32 v111, v2 offset:44352
	v_add_f32_e32 v1, v99, v51
	v_mul_f32_e32 v1, 0xbfb8aa3b, v1
	v_exp_f32_e32 v1, v1
	ds_read_u16 v3, v127
	v_add_f32_e32 v1, 1.0, v1
	v_rcp_f32_e32 v2, v1
	v_add_f32_e32 v1, v100, v47
	v_mul_f32_e32 v1, 0xbfb8aa3b, v1
	v_exp_f32_e32 v1, v1
	v_mul_f32_e32 v2, v106, v2
	v_mul_f32_e32 v2, 0x3fb8aa3b, v2
	v_exp_f32_e32 v2, v2
	v_add_f32_e32 v1, 1.0, v1
	v_rcp_f32_e32 v1, v1
	s_waitcnt lgkmcnt(0)
	v_lshlrev_b32_e32 v3, 16, v3
	v_fma_f32 v44, -v2, v2, 1.0
	v_max_f32_e32 v44, 0, v44
	v_sqrt_f32_e32 v44, v44
	v_mul_f32_e32 v1, v1, v3
	v_mul_f32_e32 v1, v44, v1
	ds_write_b32 v114, v2 offset:27712
	ds_write_b32 v114, v1 offset:44352
	ds_read_b128 v[44:47], v128 offset:9216
	ds_read_b128 v[52:55], v128 offset:9280
	s_waitcnt lgkmcnt(1)
	v_mfma_f32_16x16x32_bf16 v[44:47], v[40:43], v[44:47], 0
	ds_read_b128 v[48:51], v128 offset:18432
	ds_read_u16 v3, v129
	s_waitcnt lgkmcnt(0)
	v_lshlrev_b32_e32 v3, 16, v3
	v_mfma_f32_16x16x32_bf16 v[44:47], v[36:39], v[52:55], v[44:47]
	ds_read_b128 v[52:55], v128 offset:18496
	v_mfma_f32_16x16x32_bf16 v[48:51], v[40:43], v[48:51], 0
	s_waitcnt lgkmcnt(0)
	v_mfma_f32_16x16x32_bf16 v[48:51], v[36:39], v[52:55], v[48:51]
	s_nop 3
	v_add_f32_e32 v1, v101, v44
	v_mul_f32_e32 v1, 0xbfb8aa3b, v1
	v_exp_f32_e32 v1, v1
	s_nop 0
	v_add_f32_e32 v1, 1.0, v1
	v_rcp_f32_e32 v1, v1
	v_add_f32_e32 v2, v102, v48
	v_mul_f32_e32 v2, 0xbfb8aa3b, v2
	v_exp_f32_e32 v2, v2
	v_mul_f32_e32 v1, v107, v1
	v_mul_f32_e32 v1, 0x3fb8aa3b, v1
	v_exp_f32_e32 v1, v1
	v_add_f32_e32 v2, 1.0, v2
	v_rcp_f32_e32 v2, v2
	v_fma_f32 v44, -v1, v1, 1.0
	v_max_f32_e32 v44, 0, v44
	v_sqrt_f32_e32 v44, v44
	v_mul_f32_e32 v2, v2, v3
	v_mul_f32_e32 v2, v2, v44
	ds_write_b32 v109, v1 offset:27776
	ds_write_b32 v109, v2 offset:44416
	v_add_f32_e32 v1, v101, v45
	v_mul_f32_e32 v1, 0xbfb8aa3b, v1
	v_exp_f32_e32 v1, v1
	v_add_f32_e32 v2, v102, v49
	v_mul_f32_e32 v2, 0xbfb8aa3b, v2
	v_exp_f32_e32 v2, v2
	v_add_f32_e32 v1, 1.0, v1
	v_rcp_f32_e32 v1, v1
	ds_read_u16 v3, v130
	v_add_f32_e32 v2, 1.0, v2
	v_rcp_f32_e32 v2, v2
	v_mul_f32_e32 v1, v107, v1
	v_mul_f32_e32 v1, 0x3fb8aa3b, v1
	v_exp_f32_e32 v1, v1
	s_waitcnt lgkmcnt(0)
	v_lshlrev_b32_e32 v3, 16, v3
	v_mul_f32_e32 v2, v2, v3
	v_fma_f32 v44, -v1, v1, 1.0
	v_max_f32_e32 v44, 0, v44
	v_sqrt_f32_e32 v44, v44
	s_nop 0
	v_mul_f32_e32 v2, v2, v44
	ds_write_b32 v113, v1 offset:27776
	ds_write_b32 v113, v2 offset:44416
	v_add_f32_e32 v1, v101, v46
	v_mul_f32_e32 v1, 0xbfb8aa3b, v1
	v_exp_f32_e32 v1, v1
	v_add_f32_e32 v2, v102, v50
	v_mul_f32_e32 v2, 0xbfb8aa3b, v2
	v_exp_f32_e32 v2, v2
	v_add_f32_e32 v1, 1.0, v1
	v_rcp_f32_e32 v1, v1
	ds_read_u16 v3, v131
	v_add_f32_e32 v2, 1.0, v2
	v_rcp_f32_e32 v2, v2
	v_mul_f32_e32 v1, v107, v1
	v_mul_f32_e32 v1, 0x3fb8aa3b, v1
	v_exp_f32_e32 v1, v1
	s_waitcnt lgkmcnt(0)
	v_lshlrev_b32_e32 v3, 16, v3
	v_mul_f32_e32 v2, v2, v3
	v_fma_f32 v44, -v1, v1, 1.0
	v_max_f32_e32 v44, 0, v44
	v_sqrt_f32_e32 v44, v44
	s_nop 0
	v_mul_f32_e32 v2, v2, v44
	ds_write_b32 v111, v1 offset:27776
	ds_write_b32 v111, v2 offset:44416
	v_add_f32_e32 v1, v101, v47
	v_mul_f32_e32 v1, 0xbfb8aa3b, v1
	v_exp_f32_e32 v1, v1
	v_add_f32_e32 v2, v102, v51
	v_mul_f32_e32 v2, 0xbfb8aa3b, v2
	v_exp_f32_e32 v2, v2
	v_add_f32_e32 v1, 1.0, v1
	v_rcp_f32_e32 v1, v1
	ds_read_u16 v3, v132
	v_add_f32_e32 v2, 1.0, v2
	v_rcp_f32_e32 v2, v2
	v_mul_f32_e32 v1, v107, v1
	v_mul_f32_e32 v1, 0x3fb8aa3b, v1
	v_exp_f32_e32 v1, v1
	s_waitcnt lgkmcnt(0)
	v_lshlrev_b32_e32 v3, 16, v3
	v_mul_f32_e32 v2, v2, v3
	v_fma_f32 v44, -v1, v1, 1.0
	v_max_f32_e32 v44, 0, v44
	v_sqrt_f32_e32 v44, v44
	s_nop 0
	v_mul_f32_e32 v2, v44, v2
	ds_write_b32 v114, v1 offset:27776
	ds_write_b32 v114, v2 offset:44416
	ds_read_b128 v[44:47], v133 offset:9216
	ds_read_b128 v[48:51], v133 offset:18432
	s_waitcnt lgkmcnt(1)
	v_mfma_f32_16x16x32_bf16 v[44:47], v[40:43], v[44:47], 0
	ds_read_u16 v3, v134
	s_waitcnt lgkmcnt(0)
	v_lshlrev_b32_e32 v3, 16, v3
	v_mfma_f32_16x16x32_bf16 v[48:51], v[40:43], v[48:51], 0
	ds_read_b128 v[40:43], v133 offset:9280
	s_waitcnt lgkmcnt(0)
	v_mfma_f32_16x16x32_bf16 v[40:43], v[36:39], v[40:43], v[44:47]
	s_nop 2
	ds_read_b128 v[44:47], v133 offset:18496
	s_waitcnt lgkmcnt(0)
	v_mfma_f32_16x16x32_bf16 v[36:39], v[36:39], v[44:47], v[48:51]
	s_nop 1
	v_add_f32_e32 v1, v103, v40
	v_mul_f32_e32 v1, 0xbfb8aa3b, v1
	v_exp_f32_e32 v1, v1
	s_nop 2
	v_add_f32_e32 v2, v104, v36
	v_mul_f32_e32 v2, 0xbfb8aa3b, v2
	v_exp_f32_e32 v2, v2
	v_add_f32_e32 v1, 1.0, v1
	v_rcp_f32_e32 v1, v1
	v_add_f32_e32 v2, 1.0, v2
	v_rcp_f32_e32 v2, v2
	v_mul_f32_e32 v1, v108, v1
	v_mul_f32_e32 v1, 0x3fb8aa3b, v1
	v_exp_f32_e32 v1, v1
	v_mul_f32_e32 v2, v2, v3
	v_fma_f32 v36, -v1, v1, 1.0
	v_max_f32_e32 v36, 0, v36
	v_sqrt_f32_e32 v36, v36
	s_nop 0
	v_mul_f32_e32 v2, v2, v36
	ds_write_b32 v109, v1 offset:27840
	ds_write_b32 v109, v2 offset:44480
	v_add_f32_e32 v1, v103, v41
	v_mul_f32_e32 v1, 0xbfb8aa3b, v1
	v_exp_f32_e32 v1, v1
	v_add_f32_e32 v2, v104, v37
	v_mul_f32_e32 v2, 0xbfb8aa3b, v2
	v_exp_f32_e32 v2, v2
	v_add_f32_e32 v1, 1.0, v1
	v_rcp_f32_e32 v1, v1
	ds_read_u16 v3, v135
	v_add_f32_e32 v2, 1.0, v2
	v_rcp_f32_e32 v2, v2
	v_mul_f32_e32 v1, v108, v1
	v_mul_f32_e32 v1, 0x3fb8aa3b, v1
	v_exp_f32_e32 v1, v1
	s_waitcnt lgkmcnt(0)
	v_lshlrev_b32_e32 v3, 16, v3
	v_mul_f32_e32 v2, v2, v3
	v_fma_f32 v36, -v1, v1, 1.0
	v_max_f32_e32 v36, 0, v36
	v_sqrt_f32_e32 v36, v36
	s_nop 0
	v_mul_f32_e32 v2, v2, v36
	ds_write_b32 v113, v1 offset:27840
	ds_write_b32 v113, v2 offset:44480
	v_add_f32_e32 v1, v103, v42
	v_mul_f32_e32 v1, 0xbfb8aa3b, v1
	v_exp_f32_e32 v1, v1
	v_add_f32_e32 v2, v104, v38
	v_mul_f32_e32 v2, 0xbfb8aa3b, v2
	v_exp_f32_e32 v2, v2
	v_add_f32_e32 v1, 1.0, v1
	v_rcp_f32_e32 v1, v1
	ds_read_u16 v3, v136
	v_add_f32_e32 v2, 1.0, v2
	v_rcp_f32_e32 v2, v2
	v_mul_f32_e32 v1, v108, v1
	v_mul_f32_e32 v1, 0x3fb8aa3b, v1
	v_exp_f32_e32 v1, v1
	s_waitcnt lgkmcnt(0)
	v_lshlrev_b32_e32 v3, 16, v3
	v_mul_f32_e32 v2, v2, v3
	v_fma_f32 v36, -v1, v1, 1.0
	v_max_f32_e32 v36, 0, v36
	v_sqrt_f32_e32 v36, v36
	s_nop 0
	v_mul_f32_e32 v2, v2, v36
	ds_write_b32 v111, v1 offset:27840
	ds_write_b32 v111, v2 offset:44480
	v_add_f32_e32 v1, v103, v43
	v_mul_f32_e32 v1, 0xbfb8aa3b, v1
	v_exp_f32_e32 v1, v1
	ds_read_u16 v3, v137
	v_add_f32_e32 v1, 1.0, v1
	v_rcp_f32_e32 v2, v1
	v_add_f32_e32 v1, v104, v39
	v_mul_f32_e32 v1, 0xbfb8aa3b, v1
	v_exp_f32_e32 v1, v1
	v_mul_f32_e32 v2, v108, v2
	v_mul_f32_e32 v2, 0x3fb8aa3b, v2
	v_exp_f32_e32 v2, v2
	v_add_f32_e32 v1, 1.0, v1
	v_rcp_f32_e32 v1, v1
	s_waitcnt lgkmcnt(0)
	v_lshlrev_b32_e32 v3, 16, v3
	v_fma_f32 v36, -v2, v2, 1.0
	v_max_f32_e32 v36, 0, v36
	v_sqrt_f32_e32 v36, v36
	v_mul_f32_e32 v1, v1, v3
	v_mul_f32_e32 v1, v36, v1
	ds_write_b32 v114, v2 offset:27840
	ds_write_b32 v114, v1 offset:44480
	s_waitcnt lgkmcnt(0)
	s_cmp_lg_u32 s34, 2
	s_cbranch_scc1 .Lfg_nowait_p
	s_waitcnt vmcnt(0)
.Lfg_nowait_p:
	s_barrier
	s_cmp_lt_u32 s34, 2
	s_cbranch_scc1 .Lfg_nold_p
	s_sub_i32 s38, 3, s34
	s_and_b64 s[28:29], s[16:17], exec
	s_cselect_b32 s38, s34, s38
	s_mov_b32 s39, 0xfe000000
	s_cselect_b32 s39, 0x2000000, s39
	s_mov_b32 s41, 0x2000000
	s_cselect_b32 s41, 0x4000000, s41
	s_lshl_b32 s38, s38, 6
	s_add_i32 s38, s38, s50
	v_or_b32_e32 v202, s38, v93
	v_lshl_add_u32 v228, v202, 11, s39
	v_ashrrev_i32_e32 v229, 31, v228
	v_lshl_add_u64 v[228:229], v[78:79], 0, v[228:229]
	v_lshl_add_u32 v238, v202, 12, s41
	v_mov_b32_e32 v239, 0
	v_lshl_add_u64 v[238:239], v[78:79], 0, v[238:239]
	global_load_dwordx4 v[228:231], v[228:229], off
	global_load_dwordx4 v[238:241], v[238:239], off
	v_or_b32_e32 v202, s38, v95
	v_lshl_add_u32 v250, v202, 11, s39
	v_ashrrev_i32_e32 v251, 31, v250
	v_lshl_add_u64 v[250:251], v[78:79], 0, v[250:251]
	v_lshl_add_u32 v202, v202, 12, s41
	v_mov_b32_e32 v203, 0
	v_lshl_add_u64 v[202:203], v[78:79], 0, v[202:203]
	global_load_dwordx4 v[250:253], v[250:251], off
	global_load_dword v69, v[202:203], off
	global_load_dword v90, v[202:203], off offset:4
	global_load_dword v189, v[202:203], off offset:8
	global_load_dword v207, v[202:203], off offset:12

.LBB0_305:
	s_waitcnt lgkmcnt(0)
	s_barrier
	ds_read_b128 v[40:43], v117
	ds_read_b128 v[36:39], v117 offset:64
	ds_read_b128 v[44:47], v118 offset:9216
	ds_read_b128 v[48:51], v118 offset:18432
	ds_read_b128 v[52:55], v118 offset:9280
	s_waitcnt lgkmcnt(2)
	v_mfma_f32_16x16x32_bf16 v[44:47], v[40:43], v[44:47], 0
	ds_read_u16 v3, v119
	s_waitcnt lgkmcnt(0)
	v_lshlrev_b32_e32 v3, 16, v3
	v_mfma_f32_16x16x32_bf16 v[44:47], v[36:39], v[52:55], v[44:47]
	ds_read_b128 v[52:55], v118 offset:18496
	v_mfma_f32_16x16x32_bf16 v[48:51], v[40:43], v[48:51], 0
	s_waitcnt lgkmcnt(0)
	v_mfma_f32_16x16x32_bf16 v[48:51], v[36:39], v[52:55], v[48:51]
	s_nop 3
	v_add_f32_e32 v1, v97, v44
	v_mul_f32_e32 v1, 0xbfb8aa3b, v1
	v_exp_f32_e32 v1, v1
	s_nop 0
	v_add_f32_e32 v1, 1.0, v1
	v_rcp_f32_e32 v1, v1
	v_add_f32_e32 v2, v98, v48
	v_mul_f32_e32 v2, 0xbfb8aa3b, v2
	v_exp_f32_e32 v2, v2
	v_mul_f32_e32 v1, v105, v1
	v_mul_f32_e32 v1, 0x3fb8aa3b, v1
	v_exp_f32_e32 v1, v1
	v_add_f32_e32 v2, 1.0, v2
	v_rcp_f32_e32 v2, v2
	v_fma_f32 v44, -v1, v1, 1.0
	v_max_f32_e32 v44, 0, v44
	v_sqrt_f32_e32 v44, v44
	v_mul_f32_e32 v2, v2, v3
	v_mul_f32_e32 v2, v2, v44
	ds_write_b32 v109, v1 offset:27648
	ds_write_b32 v109, v2 offset:44288
	v_add_f32_e32 v1, v97, v45
	v_mul_f32_e32 v1, 0xbfb8aa3b, v1
	v_exp_f32_e32 v1, v1
	v_add_f32_e32 v2, v98, v49
	v_mul_f32_e32 v2, 0xbfb8aa3b, v2
	v_exp_f32_e32 v2, v2
	v_add_f32_e32 v1, 1.0, v1
	v_rcp_f32_e32 v1, v1
	ds_read_u16 v3, v120
	v_add_f32_e32 v2, 1.0, v2
	v_rcp_f32_e32 v2, v2
	v_mul_f32_e32 v1, v105, v1
	v_mul_f32_e32 v1, 0x3fb8aa3b, v1
	v_exp_f32_e32 v1, v1
	s_waitcnt lgkmcnt(0)
	v_lshlrev_b32_e32 v3, 16, v3
	v_mul_f32_e32 v2, v2, v3
	ds_read_u16 v3, v121
	v_fma_f32 v44, -v1, v1, 1.0
	v_max_f32_e32 v44, 0, v44
	v_sqrt_f32_e32 v44, v44
	s_waitcnt lgkmcnt(0)
	v_lshlrev_b32_e32 v3, 16, v3
	v_mul_f32_e32 v2, v2, v44
	ds_write2st64_b32 v110, v1, v2 offset0:108 offset1:173
	v_add_f32_e32 v1, v97, v46
	v_mul_f32_e32 v1, 0xbfb8aa3b, v1
	v_exp_f32_e32 v1, v1
	v_add_f32_e32 v2, v98, v50
	v_mul_f32_e32 v2, 0xbfb8aa3b, v2
	v_exp_f32_e32 v2, v2
	v_add_f32_e32 v1, 1.0, v1
	v_rcp_f32_e32 v1, v1
	v_add_f32_e32 v2, 1.0, v2
	v_rcp_f32_e32 v2, v2
	v_mul_f32_e32 v1, v105, v1
	v_mul_f32_e32 v1, 0x3fb8aa3b, v1
	v_exp_f32_e32 v1, v1
	v_mul_f32_e32 v2, v2, v3
	v_fma_f32 v44, -v1, v1, 1.0
	v_max_f32_e32 v44, 0, v44
	v_sqrt_f32_e32 v44, v44
	s_nop 0
	v_mul_f32_e32 v2, v2, v44
	ds_write_b32 v111, v1 offset:27648
	ds_write_b32 v111, v2 offset:44288
	v_add_f32_e32 v1, v97, v47
	v_mul_f32_e32 v1, 0xbfb8aa3b, v1
	v_exp_f32_e32 v1, v1
	v_add_f32_e32 v2, v98, v51
	v_mul_f32_e32 v2, 0xbfb8aa3b, v2
	v_exp_f32_e32 v2, v2
	v_add_f32_e32 v1, 1.0, v1
	v_rcp_f32_e32 v1, v1
	ds_read_u16 v3, v122
	v_add_f32_e32 v2, 1.0, v2
	v_rcp_f32_e32 v2, v2
	v_mul_f32_e32 v1, v105, v1
	v_mul_f32_e32 v1, 0x3fb8aa3b, v1
	v_exp_f32_e32 v1, v1
	s_waitcnt lgkmcnt(0)
	v_lshlrev_b32_e32 v3, 16, v3
	v_mul_f32_e32 v2, v2, v3
	ds_read_u16 v3, v124
	v_fma_f32 v44, -v1, v1, 1.0
	v_max_f32_e32 v44, 0, v44
	v_sqrt_f32_e32 v44, v44
	s_waitcnt lgkmcnt(0)
	v_lshlrev_b32_e32 v3, 16, v3
	v_mul_f32_e32 v2, v44, v2
	ds_write2st64_b32 v112, v1, v2 offset0:108 offset1:173
	ds_read_b128 v[48:51], v123 offset:18432
	ds_read_b128 v[44:47], v123 offset:9216
	s_waitcnt lgkmcnt(1)
	v_mfma_f32_16x16x32_bf16 v[52:55], v[40:43], v[48:51], 0
	ds_read_b128 v[48:51], v123 offset:9280
	s_waitcnt lgkmcnt(1)
	v_mfma_f32_16x16x32_bf16 v[44:47], v[40:43], v[44:47], 0
	s_waitcnt lgkmcnt(0)
	v_mfma_f32_16x16x32_bf16 v[48:51], v[36:39], v[48:51], v[44:47]
	s_nop 5
	ds_read_b128 v[44:47], v123 offset:18496
	s_nop 0
	v_add_f32_e32 v1, v99, v48
	v_mul_f32_e32 v1, 0xbfb8aa3b, v1
	v_exp_f32_e32 v1, v1
	s_waitcnt lgkmcnt(0)
	v_mfma_f32_16x16x32_bf16 v[44:47], v[36:39], v[44:47], v[52:55]
	v_add_f32_e32 v1, 1.0, v1
	v_rcp_f32_e32 v1, v1
	s_nop 0
	v_mul_f32_e32 v1, v106, v1
	s_nop 3
	v_add_f32_e32 v2, v100, v44
	v_mul_f32_e32 v2, 0xbfb8aa3b, v2
	v_mul_f32_e32 v1, 0x3fb8aa3b, v1
	v_exp_f32_e32 v2, v2
	v_exp_f32_e32 v1, v1
	v_add_f32_e32 v2, 1.0, v2
	v_fma_f32 v44, -v1, v1, 1.0
	v_rcp_f32_e32 v2, v2
	v_max_f32_e32 v44, 0, v44
	v_sqrt_f32_e32 v44, v44
	v_mul_f32_e32 v2, v2, v3
	v_mul_f32_e32 v2, v2, v44
	ds_write_b32 v109, v1 offset:27712
	ds_write_b32 v109, v2 offset:44352
	v_add_f32_e32 v1, v99, v49
	v_mul_f32_e32 v1, 0xbfb8aa3b, v1
	v_exp_f32_e32 v1, v1
	v_add_f32_e32 v2, v100, v45
	v_mul_f32_e32 v2, 0xbfb8aa3b, v2
	v_exp_f32_e32 v2, v2
	v_add_f32_e32 v1, 1.0, v1
	v_rcp_f32_e32 v1, v1
	ds_read_u16 v3, v125
	v_add_f32_e32 v2, 1.0, v2
	v_rcp_f32_e32 v2, v2
	v_mul_f32_e32 v1, v106, v1
	v_mul_f32_e32 v1, 0x3fb8aa3b, v1
	v_exp_f32_e32 v1, v1
	s_waitcnt lgkmcnt(0)
	v_lshlrev_b32_e32 v3, 16, v3
	v_mul_f32_e32 v2, v2, v3
	v_fma_f32 v44, -v1, v1, 1.0
	v_max_f32_e32 v44, 0, v44
	v_sqrt_f32_e32 v44, v44
	s_nop 0
	v_mul_f32_e32 v2, v2, v44
	ds_write_b32 v113, v1 offset:27712
	ds_write_b32 v113, v2 offset:44352
	v_add_f32_e32 v1, v99, v50
	v_mul_f32_e32 v1, 0xbfb8aa3b, v1
	v_exp_f32_e32 v1, v1
	v_add_f32_e32 v2, v100, v46
	v_mul_f32_e32 v2, 0xbfb8aa3b, v2
	v_exp_f32_e32 v2, v2
	v_add_f32_e32 v1, 1.0, v1
	v_rcp_f32_e32 v1, v1
	ds_read_u16 v3, v126
	v_add_f32_e32 v2, 1.0, v2
	v_rcp_f32_e32 v2, v2
	v_mul_f32_e32 v1, v106, v1
	v_mul_f32_e32 v1, 0x3fb8aa3b, v1
	v_exp_f32_e32 v1, v1
	s_waitcnt lgkmcnt(0)
	v_lshlrev_b32_e32 v3, 16, v3
	v_mul_f32_e32 v2, v2, v3
	v_fma_f32 v44, -v1, v1, 1.0
	v_max_f32_e32 v44, 0, v44
	v_sqrt_f32_e32 v44, v44
	s_nop 0
	v_mul_f32_e32 v2, v2, v44
	ds_write_b32 v111, v1 offset:27712
	ds_write_b32 v111, v2 offset:44352
	v_add_f32_e32 v1, v99, v51
	v_mul_f32_e32 v1, 0xbfb8aa3b, v1
	v_exp_f32_e32 v1, v1
	ds_read_u16 v3, v127
	v_add_f32_e32 v1, 1.0, v1
	v_rcp_f32_e32 v2, v1
	v_add_f32_e32 v1, v100, v47
	v_mul_f32_e32 v1, 0xbfb8aa3b, v1
	v_exp_f32_e32 v1, v1
	v_mul_f32_e32 v2, v106, v2
	v_mul_f32_e32 v2, 0x3fb8aa3b, v2
	v_exp_f32_e32 v2, v2
	v_add_f32_e32 v1, 1.0, v1
	v_rcp_f32_e32 v1, v1
	s_waitcnt lgkmcnt(0)
	v_lshlrev_b32_e32 v3, 16, v3
	v_fma_f32 v44, -v2, v2, 1.0
	v_max_f32_e32 v44, 0, v44
	v_sqrt_f32_e32 v44, v44
	v_mul_f32_e32 v1, v1, v3
	v_mul_f32_e32 v1, v44, v1
	ds_write_b32 v114, v2 offset:27712
	ds_write_b32 v114, v1 offset:44352
	ds_read_b128 v[44:47], v128 offset:9216
	ds_read_b128 v[52:55], v128 offset:9280
	s_waitcnt lgkmcnt(1)
	v_mfma_f32_16x16x32_bf16 v[44:47], v[40:43], v[44:47], 0
	ds_read_b128 v[48:51], v128 offset:18432
	ds_read_u16 v3, v129
	s_waitcnt lgkmcnt(0)
	v_lshlrev_b32_e32 v3, 16, v3
	v_mfma_f32_16x16x32_bf16 v[44:47], v[36:39], v[52:55], v[44:47]
	ds_read_b128 v[52:55], v128 offset:18496
	v_mfma_f32_16x16x32_bf16 v[48:51], v[40:43], v[48:51], 0
	s_waitcnt lgkmcnt(0)
	v_mfma_f32_16x16x32_bf16 v[48:51], v[36:39], v[52:55], v[48:51]
	s_nop 3
	v_add_f32_e32 v1, v101, v44
	v_mul_f32_e32 v1, 0xbfb8aa3b, v1
	v_exp_f32_e32 v1, v1
	s_nop 0
	v_add_f32_e32 v1, 1.0, v1
	v_rcp_f32_e32 v1, v1
	v_add_f32_e32 v2, v102, v48
	v_mul_f32_e32 v2, 0xbfb8aa3b, v2
	v_exp_f32_e32 v2, v2
	v_mul_f32_e32 v1, v107, v1
	v_mul_f32_e32 v1, 0x3fb8aa3b, v1
	v_exp_f32_e32 v1, v1
	v_add_f32_e32 v2, 1.0, v2
	v_rcp_f32_e32 v2, v2
	v_fma_f32 v44, -v1, v1, 1.0
	v_max_f32_e32 v44, 0, v44
	v_sqrt_f32_e32 v44, v44
	v_mul_f32_e32 v2, v2, v3
	v_mul_f32_e32 v2, v2, v44
	ds_write_b32 v109, v1 offset:27776
	ds_write_b32 v109, v2 offset:44416
	v_add_f32_e32 v1, v101, v45
	v_mul_f32_e32 v1, 0xbfb8aa3b, v1
	v_exp_f32_e32 v1, v1
	v_add_f32_e32 v2, v102, v49
	v_mul_f32_e32 v2, 0xbfb8aa3b, v2
	v_exp_f32_e32 v2, v2
	v_add_f32_e32 v1, 1.0, v1
	v_rcp_f32_e32 v1, v1
	ds_read_u16 v3, v130
	v_add_f32_e32 v2, 1.0, v2
	v_rcp_f32_e32 v2, v2
	v_mul_f32_e32 v1, v107, v1
	v_mul_f32_e32 v1, 0x3fb8aa3b, v1
	v_exp_f32_e32 v1, v1
	s_waitcnt lgkmcnt(0)
	v_lshlrev_b32_e32 v3, 16, v3
	v_mul_f32_e32 v2, v2, v3
	v_fma_f32 v44, -v1, v1, 1.0
	v_max_f32_e32 v44, 0, v44
	v_sqrt_f32_e32 v44, v44
	s_nop 0
	v_mul_f32_e32 v2, v2, v44
	ds_write_b32 v113, v1 offset:27776
	ds_write_b32 v113, v2 offset:44416
	v_add_f32_e32 v1, v101, v46
	v_mul_f32_e32 v1, 0xbfb8aa3b, v1
	v_exp_f32_e32 v1, v1
	v_add_f32_e32 v2, v102, v50
	v_mul_f32_e32 v2, 0xbfb8aa3b, v2
	v_exp_f32_e32 v2, v2
	v_add_f32_e32 v1, 1.0, v1
	v_rcp_f32_e32 v1, v1
	ds_read_u16 v3, v131
	v_add_f32_e32 v2, 1.0, v2
	v_rcp_f32_e32 v2, v2
	v_mul_f32_e32 v1, v107, v1
	v_mul_f32_e32 v1, 0x3fb8aa3b, v1
	v_exp_f32_e32 v1, v1
	s_waitcnt lgkmcnt(0)
	v_lshlrev_b32_e32 v3, 16, v3
	v_mul_f32_e32 v2, v2, v3
	v_fma_f32 v44, -v1, v1, 1.0
	v_max_f32_e32 v44, 0, v44
	v_sqrt_f32_e32 v44, v44
	s_nop 0
	v_mul_f32_e32 v2, v2, v44
	ds_write_b32 v111, v1 offset:27776
	ds_write_b32 v111, v2 offset:44416
	v_add_f32_e32 v1, v101, v47
	v_mul_f32_e32 v1, 0xbfb8aa3b, v1
	v_exp_f32_e32 v1, v1
	v_add_f32_e32 v2, v102, v51
	v_mul_f32_e32 v2, 0xbfb8aa3b, v2
	v_exp_f32_e32 v2, v2
	v_add_f32_e32 v1, 1.0, v1
	v_rcp_f32_e32 v1, v1
	ds_read_u16 v3, v132
	v_add_f32_e32 v2, 1.0, v2
	v_rcp_f32_e32 v2, v2
	v_mul_f32_e32 v1, v107, v1
	v_mul_f32_e32 v1, 0x3fb8aa3b, v1
	v_exp_f32_e32 v1, v1
	s_waitcnt lgkmcnt(0)
	v_lshlrev_b32_e32 v3, 16, v3
	v_mul_f32_e32 v2, v2, v3
	v_fma_f32 v44, -v1, v1, 1.0
	v_max_f32_e32 v44, 0, v44
	v_sqrt_f32_e32 v44, v44
	s_nop 0
	v_mul_f32_e32 v2, v44, v2
	ds_write_b32 v114, v1 offset:27776
	ds_write_b32 v114, v2 offset:44416
	ds_read_b128 v[44:47], v133 offset:9216
	ds_read_b128 v[48:51], v133 offset:18432
	s_waitcnt lgkmcnt(1)
	v_mfma_f32_16x16x32_bf16 v[44:47], v[40:43], v[44:47], 0
	ds_read_u16 v3, v134
	s_waitcnt lgkmcnt(0)
	v_lshlrev_b32_e32 v3, 16, v3
	v_mfma_f32_16x16x32_bf16 v[48:51], v[40:43], v[48:51], 0
	ds_read_b128 v[40:43], v133 offset:9280
	s_waitcnt lgkmcnt(0)
	v_mfma_f32_16x16x32_bf16 v[40:43], v[36:39], v[40:43], v[44:47]
	s_nop 2
	ds_read_b128 v[44:47], v133 offset:18496
	s_waitcnt lgkmcnt(0)
	v_mfma_f32_16x16x32_bf16 v[36:39], v[36:39], v[44:47], v[48:51]
	s_nop 1
	v_add_f32_e32 v1, v103, v40
	v_mul_f32_e32 v1, 0xbfb8aa3b, v1
	v_exp_f32_e32 v1, v1
	s_nop 2
	v_add_f32_e32 v2, v104, v36
	v_mul_f32_e32 v2, 0xbfb8aa3b, v2
	v_exp_f32_e32 v2, v2
	v_add_f32_e32 v1, 1.0, v1
	v_rcp_f32_e32 v1, v1
	v_add_f32_e32 v2, 1.0, v2
	v_rcp_f32_e32 v2, v2
	v_mul_f32_e32 v1, v108, v1
	v_mul_f32_e32 v1, 0x3fb8aa3b, v1
	v_exp_f32_e32 v1, v1
	v_mul_f32_e32 v2, v2, v3
	v_fma_f32 v36, -v1, v1, 1.0
	v_max_f32_e32 v36, 0, v36
	v_sqrt_f32_e32 v36, v36
	s_nop 0
	v_mul_f32_e32 v2, v2, v36
	ds_write_b32 v109, v1 offset:27840
	ds_write_b32 v109, v2 offset:44480
	v_add_f32_e32 v1, v103, v41
	v_mul_f32_e32 v1, 0xbfb8aa3b, v1
	v_exp_f32_e32 v1, v1
	v_add_f32_e32 v2, v104, v37
	v_mul_f32_e32 v2, 0xbfb8aa3b, v2
	v_exp_f32_e32 v2, v2
	v_add_f32_e32 v1, 1.0, v1
	v_rcp_f32_e32 v1, v1
	ds_read_u16 v3, v135
	v_add_f32_e32 v2, 1.0, v2
	v_rcp_f32_e32 v2, v2
	v_mul_f32_e32 v1, v108, v1
	v_mul_f32_e32 v1, 0x3fb8aa3b, v1
	v_exp_f32_e32 v1, v1
	s_waitcnt lgkmcnt(0)
	v_lshlrev_b32_e32 v3, 16, v3
	v_mul_f32_e32 v2, v2, v3
	v_fma_f32 v36, -v1, v1, 1.0
	v_max_f32_e32 v36, 0, v36
	v_sqrt_f32_e32 v36, v36
	s_nop 0
	v_mul_f32_e32 v2, v2, v36
	ds_write_b32 v113, v1 offset:27840
	ds_write_b32 v113, v2 offset:44480
	v_add_f32_e32 v1, v103, v42
	v_mul_f32_e32 v1, 0xbfb8aa3b, v1
	v_exp_f32_e32 v1, v1
	v_add_f32_e32 v2, v104, v38
	v_mul_f32_e32 v2, 0xbfb8aa3b, v2
	v_exp_f32_e32 v2, v2
	v_add_f32_e32 v1, 1.0, v1
	v_rcp_f32_e32 v1, v1
	ds_read_u16 v3, v136
	v_add_f32_e32 v2, 1.0, v2
	v_rcp_f32_e32 v2, v2
	v_mul_f32_e32 v1, v108, v1
	v_mul_f32_e32 v1, 0x3fb8aa3b, v1
	v_exp_f32_e32 v1, v1
	s_waitcnt lgkmcnt(0)
	v_lshlrev_b32_e32 v3, 16, v3
	v_mul_f32_e32 v2, v2, v3
	v_fma_f32 v36, -v1, v1, 1.0
	v_max_f32_e32 v36, 0, v36
	v_sqrt_f32_e32 v36, v36
	s_nop 0
	v_mul_f32_e32 v2, v2, v36
	ds_write_b32 v111, v1 offset:27840
	ds_write_b32 v111, v2 offset:44480
	v_add_f32_e32 v1, v103, v43
	v_mul_f32_e32 v1, 0xbfb8aa3b, v1
	v_exp_f32_e32 v1, v1
	ds_read_u16 v3, v137
	v_add_f32_e32 v1, 1.0, v1
	v_rcp_f32_e32 v2, v1
	v_add_f32_e32 v1, v104, v39
	v_mul_f32_e32 v1, 0xbfb8aa3b, v1
	v_exp_f32_e32 v1, v1
	v_mul_f32_e32 v2, v108, v2
	v_mul_f32_e32 v2, 0x3fb8aa3b, v2
	v_exp_f32_e32 v2, v2
	v_add_f32_e32 v1, 1.0, v1
	v_rcp_f32_e32 v1, v1
	s_waitcnt lgkmcnt(0)
	v_lshlrev_b32_e32 v3, 16, v3
	v_fma_f32 v36, -v2, v2, 1.0
	v_max_f32_e32 v36, 0, v36
	v_sqrt_f32_e32 v36, v36
	v_mul_f32_e32 v1, v1, v3
	v_mul_f32_e32 v1, v36, v1
	ds_write_b32 v114, v2 offset:27840
	ds_write_b32 v114, v1 offset:44480
	s_waitcnt lgkmcnt(0)
	s_cmp_lg_u32 s20, 8
	s_cbranch_scc1 .Lfg_nowait_s
	s_waitcnt vmcnt(0)
.Lfg_nowait_s:
	s_barrier
	s_cmp_lt_u32 s20, 8
	s_cbranch_scc1 .Lfg_nold_s
	s_sub_i32 s38, 15, s20
	s_and_b64 s[18:19], s[12:13], exec
	s_cselect_b32 s38, s20, s38
	s_mov_b32 s39, 0xfe000000
	s_cselect_b32 s39, 0x2000000, s39
	s_mov_b32 s41, 0x2000000
	s_cselect_b32 s41, 0x4000000, s41
	s_lshl_b32 s38, s38, 6
	s_add_i32 s38, s38, s34
	v_or_b32_e32 v202, s38, v93
	v_lshl_add_u32 v228, v202, 11, s39
	v_ashrrev_i32_e32 v229, 31, v228
	v_lshl_add_u64 v[228:229], v[78:79], 0, v[228:229]
	v_lshl_add_u32 v238, v202, 12, s41
	v_mov_b32_e32 v239, 0
	v_lshl_add_u64 v[238:239], v[78:79], 0, v[238:239]
	global_load_dwordx4 v[228:231], v[228:229], off
	global_load_dwordx4 v[238:241], v[238:239], off
	v_or_b32_e32 v202, s38, v95
	v_lshl_add_u32 v250, v202, 11, s39
	v_ashrrev_i32_e32 v251, 31, v250
	v_lshl_add_u64 v[250:251], v[78:79], 0, v[250:251]
	v_lshl_add_u32 v202, v202, 12, s41
	v_mov_b32_e32 v203, 0
	v_lshl_add_u64 v[202:203], v[78:79], 0, v[202:203]
	global_load_dwordx4 v[250:253], v[250:251], off
	global_load_dword v69, v[202:203], off
	global_load_dword v90, v[202:203], off offset:4
	global_load_dword v189, v[202:203], off offset:8
	global_load_dword v207, v[202:203], off offset:12
